# static priority raise (s_setprio 1) for waves 0-3 across the attention phases, reset at the phase exit
# baseline (speedup 1.0000x reference)
.LBB0_941:
	s_or_b64 exec, exec, s[0:1]
	s_mov_b32 s22, s83
	s_mov_b32 s94, s90
	s_mov_b64 s[0:1], s[96:97]
	s_mov_b32 s95, s92
	s_waitcnt lgkmcnt(0)
	s_barrier
	v_mov_b32_e32 v2, v202
	s_cmpk_gt_i32 s94, 0x1ff
	s_cbranch_scc1 .LBB0_1002
	s_load_dwordx2 s[0:1], s[0:1], 0xa0
	v_and_b32_e32 v11, 7, v2
	v_lshlrev_b32_e32 v0, 4, v11
	v_mov_b32_e32 v1, 0
	s_mov_b64 s[4:5], 0x800000
	s_waitcnt lgkmcnt(0)
	s_add_u32 s82, s0, 0x8600000
	s_addc_u32 s83, s1, 0
	s_add_u32 s84, s0, 0x11000000
	s_addc_u32 s85, s1, 0
	s_lshl_b32 s2, s22, 5
	v_lshl_add_u64 v[4:5], s[0:1], 0, v[0:1]
	s_ashr_i32 s96, s22, 1
	v_ashrrev_i32_e32 v9, 5, v2
	s_and_b32 s2, s2, 32
	v_lshl_add_u64 v[112:113], v[4:5], 0, s[4:5]
	s_mov_b64 s[4:5], 0x880000
	v_lshl_add_u64 v[114:115], v[4:5], 0, s[4:5]
	s_add_u32 s4, s0, 0x9600000
	v_lshlrev_b32_e32 v116, 3, v9
	v_lshlrev_b32_e32 v136, 4, v9
	v_lshlrev_b32_e32 v118, 2, v9
	v_and_b32_e32 v9, 64, v202
	v_lshlrev_b32_e32 v200, 2, v11
	v_writelane_b32 v254, s4, 15
	s_addc_u32 s4, s1, 0
	v_add_u32_e32 v9, 64, v9
	v_xor_b32_e32 v18, 32, v202
	v_or_b32_e32 v215, 2, v200
	v_writelane_b32 v254, s4, 17
	v_cmp_lt_i32_e32 vcc, v18, v9
	s_lshl_b32 s4, s96, 6
	v_cmp_lt_u32_e64 s[24:25], 5, v215
	v_lshlrev_b32_e32 v3, 2, v2
	v_lshl_add_u32 v8, s22, 6, v2
	v_and_b32_e32 v14, 31, v2
	v_and_b32_e32 v15, 16, v2
	v_cndmask_b32_e32 v18, v202, v18, vcc
	s_or_b32 s4, s4, s2
	v_writelane_b32 v254, s24, 19
	v_add_u32_e32 v123, 0, v0
	v_ashrrev_i32_e32 v0, 3, v8
	v_lshlrev_b32_e32 v196, 2, v18
	v_or_b32_e32 v18, s4, v14
	s_movk_i32 s7, 0x84
	v_and_or_b32 v15, v3, 12, v15
	v_writelane_b32 v254, s25, 20
	v_cmp_lt_u32_e64 s[24:25], 9, v215
	v_mul_lo_u32 v18, v18, s7
	v_lshlrev_b32_e32 v198, 1, v15
	v_lshl_add_u32 v15, v0, 5, v0
	v_writelane_b32 v254, s24, 21
	v_add3_u32 v197, 0, v18, v118
	v_add_u32_e32 v18, v15, v200
	s_add_i32 s8, 0, 0x18000
	v_or_b32_e32 v213, 1, v200
	v_writelane_b32 v254, s25, 22
	v_cmp_lt_u32_e64 s[24:25], 13, v215
	v_lshrrev_b32_e32 v10, 2, v2
	v_add_u32_e32 v6, 0x200, v8
	v_lshl_add_u32 v212, v18, 2, s8
	v_add_u32_e32 v18, v15, v213
	v_or_b32_e32 v217, 3, v200
	v_writelane_b32 v254, s24, 23
	s_movk_i32 s23, 0x90
	s_movk_i32 s6, 0xc0
	v_ashrrev_i32_e32 v12, 3, v6
	v_and_or_b32 v10, v10, 3, v118
	v_lshl_add_u32 v214, v18, 2, s8
	v_add_u32_e32 v18, v15, v215
	v_add_u32_e32 v15, v15, v217
	v_writelane_b32 v254, s25, 24
	v_cmp_lt_u32_e64 s[24:25], 17, v215
	v_cmp_lt_i32_e32 vcc, v208, v9
	v_mul_lo_u32 v135, v0, s6
	v_lshlrev_b32_e32 v6, 6, v12
	v_mul_lo_u32 v13, v12, s23
	v_mul_lo_u32 v12, v12, s6
	v_mul_lo_u32 v10, v10, s6
	v_mul_lo_u32 v201, v0, s7
	v_cmp_eq_u32_e64 s[6:7], 0, v11
	v_lshl_add_u32 v216, v18, 2, s8
	v_lshl_add_u32 v218, v15, 2, s8
	v_cmp_ne_u32_e64 s[8:9], 0, v11
	v_cmp_lt_u32_e64 s[10:11], 1, v11
	v_cmp_lt_u32_e64 s[12:13], 2, v11
	v_cmp_lt_u32_e64 s[14:15], 3, v11
	v_cmp_lt_u32_e64 s[16:17], 4, v11
	v_cmp_lt_u32_e64 s[18:19], 5, v11
	v_cmp_eq_u32_e64 s[20:21], 7, v11
	v_writelane_b32 v254, s24, 25
	v_cndmask_b32_e32 v11, v202, v208, vcc
	v_cmp_lt_i32_e32 vcc, v203, v9
	s_lshl_b32 s22, s22, 13
	v_writelane_b32 v254, s25, 26
	v_lshlrev_b32_e32 v219, 2, v11
	v_cndmask_b32_e32 v11, v202, v203, vcc
	v_cmp_lt_i32_e32 vcc, v209, v9
	s_add_i32 s24, 0, 0x1a100
	s_lshl_b32 s25, s2, 2
	s_add_i32 s22, s22, 0
	v_lshlrev_b32_e32 v220, 2, v11
	v_cndmask_b32_e32 v11, v202, v209, vcc
	v_lshl_add_u32 v222, v0, 2, s24
	v_lshl_add_u32 v223, v8, 2, s24
	s_add_i32 s24, s24, s25
	v_add_u32_e32 v227, s22, v3
	s_movk_i32 s22, 0x300
	v_lshlrev_b32_e32 v221, 2, v11
	v_xor_b32_e32 v11, 8, v202
	v_lshl_add_u32 v226, v14, 2, s24
	v_mul_lo_u32 v3, v0, s22
	s_add_i32 s22, 0, 0x1a400
	s_add_i32 s24, 0, 0x1c800
	v_cmp_lt_i32_e32 vcc, v11, v9
	v_xor_b32_e32 v15, 16, v202
	s_add_u32 s86, s0, 0x6600000
	v_mul_lo_u32 v134, v0, s23
	v_cndmask_b32_e32 v11, v202, v11, vcc
	v_cmp_lt_i32_e32 vcc, v15, v9
	v_cmp_gt_i32_e64 s[76:77], 64, v8
	s_addc_u32 s87, s1, 0
	v_cmp_eq_u32_e64 s[0:1], 0, v8
	v_lshlrev_b32_e32 v8, 3, v2
	v_lshlrev_b32_e32 v4, 6, v0
	v_cmp_gt_u32_e64 s[4:5], 32, v2
	v_cndmask_b32_e32 v9, v202, v15, vcc
	v_writelane_b32 v254, s0, 27
	v_and_or_b32 v3, v8, 56, v3
	v_add_u32_e32 v122, 0, v134
	v_lshlrev_b32_e32 v2, 4, v2
	v_ashrrev_i32_e32 v5, 31, v4
	v_ashrrev_i32_e32 v7, 31, v6
	v_add_u32_e32 v16, 0, v136
	v_mul_u32_u24_e32 v17, 0x90, v14
	v_add_u32_e32 v210, v123, v201
	v_lshlrev_b32_e32 v224, 2, v11
	v_lshlrev_b32_e32 v225, 2, v9
	v_add_u32_e32 v9, s22, v134
	v_mad_u32_u24 v11, v14, s23, 0
	v_mov_b32_e32 v15, s22
	v_writelane_b32 v254, s1, 28
	v_lshlrev_b32_e32 v120, 1, v3
	v_and_b32_e32 v229, 0x70, v2
	v_mad_u64_u32 v[2:3], s[0:1], v0, 48, v[122:123]
	v_add_u32_e32 v0, s24, v135
	s_mov_b32 s3, 0
	v_ashrrev_i32_e32 v117, 31, v116
	v_or_b32_e32 v137, 2, v118
	v_or_b32_e32 v138, 3, v118
	v_add_u32_e32 v139, 8, v118
	v_add_u32_e32 v140, 9, v118
	v_add_u32_e32 v141, 10, v118
	v_add_u32_e32 v142, 11, v118
	v_add_u32_e32 v143, 16, v118
	v_add_u32_e32 v144, 17, v118
	v_add_u32_e32 v145, 18, v118
	v_add_u32_e32 v146, 19, v118
	v_add_u32_e32 v147, 24, v118
	v_add_u32_e32 v148, 25, v118
	v_add_u32_e32 v149, 26, v118
	v_add_u32_e32 v150, 27, v118
	v_add_u32_e32 v151, 32, v118
	v_add_u32_e32 v152, 34, v118
	v_add_u32_e32 v153, 35, v118
	v_add_u32_e32 v154, 40, v118
	v_add_u32_e32 v155, 41, v118
	v_add_u32_e32 v156, 42, v118
	v_add_u32_e32 v157, 43, v118
	v_add_u32_e32 v158, 48, v118
	v_add_u32_e32 v159, 49, v118
	v_add_u32_e32 v160, 50, v118
	v_add_u32_e32 v161, 51, v118
	v_add_u32_e32 v162, 56, v118
	v_add_u32_e32 v163, 57, v118
	v_add_u32_e32 v164, 58, v118
	v_add_u32_e32 v165, 59, v118
	v_add_u32_e32 v166, 64, v118
	v_add_u32_e32 v167, 0x42, v118
	v_add_u32_e32 v168, 0x43, v118
	v_add_u32_e32 v169, 0x48, v118
	v_add_u32_e32 v170, 0x49, v118
	v_add_u32_e32 v171, 0x4a, v118
	v_add_u32_e32 v172, 0x4b, v118
	v_add_u32_e32 v173, 0x50, v118
	v_add_u32_e32 v174, 0x51, v118
	v_add_u32_e32 v175, 0x52, v118
	v_add_u32_e32 v176, 0x53, v118
	v_add_u32_e32 v177, 0x58, v118
	v_add_u32_e32 v178, 0x59, v118
	v_add_u32_e32 v179, 0x5a, v118
	v_add_u32_e32 v180, 0x5b, v118
	v_add_u32_e32 v181, 0x60, v118
	v_add_u32_e32 v182, 0x62, v118
	v_add_u32_e32 v183, 0x63, v118
	v_add_u32_e32 v184, 0x68, v118
	v_add_u32_e32 v185, 0x69, v118
	v_add_u32_e32 v186, 0x6a, v118
	v_add_u32_e32 v187, 0x6b, v118
	v_add_u32_e32 v188, 0x70, v118
	v_add_u32_e32 v189, 0x71, v118
	v_add_u32_e32 v190, 0x72, v118
	v_add_u32_e32 v191, 0x73, v118
	v_add_u32_e32 v192, 0x78, v118
	v_add_u32_e32 v193, 0x79, v118
	v_add_u32_e32 v194, 0x7a, v118
	v_add_u32_e32 v195, 0x7b, v118
	v_add3_u32 v199, 0, v10, v198
	v_add_u32_e32 v211, 0xfc00, v210
	v_cmp_lt_u32_e64 s[30:31], 21, v215
	v_cmp_lt_u32_e64 s[34:35], 25, v215
	v_cmp_lt_u32_e64 s[36:37], 4, v217
	v_cmp_lt_u32_e64 s[38:39], 5, v217
	v_cmp_lt_u32_e64 s[40:41], 6, v217
	v_cmp_lt_u32_e64 s[42:43], 8, v217
	v_cmp_lt_u32_e64 s[44:45], 9, v217
	v_cmp_lt_u32_e64 s[46:47], 10, v217
	v_cmp_lt_u32_e64 s[48:49], 12, v217
	v_cmp_lt_u32_e64 s[50:51], 13, v217
	v_cmp_lt_u32_e64 s[52:53], 14, v217
	v_cmp_lt_u32_e64 s[54:55], 16, v217
	v_cmp_lt_u32_e64 s[56:57], 17, v217
	v_cmp_lt_u32_e64 s[58:59], 18, v217
	v_cmp_lt_u32_e64 s[60:61], 20, v217
	v_cmp_lt_u32_e64 s[62:63], 21, v217
	v_cmp_lt_u32_e64 s[64:65], 22, v217
	v_cmp_lt_u32_e64 s[66:67], 24, v217
	v_cmp_lt_u32_e64 s[68:69], 25, v217
	v_cmp_lt_u32_e64 s[70:71], 26, v217
	v_cmp_lt_u32_e64 s[72:73], 28, v217
	v_cmp_lt_u32_e64 s[74:75], 29, v217
	v_mad_u32_u24 v228, v14, s23, v15
	v_mov_b32_e32 v121, v1
	v_add_u32_e32 v230, s24, v10
	v_add_u32_e32 v231, 33, v118
	v_ashrrev_i32_e32 v119, 31, v118
	v_or_b32_e32 v232, s2, v14
	v_lshlrev_b64 v[124:125], 1, v[4:5]
	v_lshlrev_b64 v[126:127], 1, v[6:7]
	v_add_u32_e32 v233, v123, v13
	v_add_u32_e32 v234, v123, v12
	v_add_u32_e32 v235, v16, v17
	s_add_i32 s78, 0, 0x1a200
	v_mov_b32_e32 v236, 0xf149f2ca
	v_mov_b32_e32 v237, 0xc61c4000
	v_mov_b32_e32 v238, 0x461c4000
	v_add_u32_e32 v239, v2, v229
	v_add_u32_e32 v240, v9, v229
	v_add_u32_e32 v241, v0, v229
	v_add_u32_e32 v242, v11, v136
	v_readlane_b32 s32, v254, 3
	s_cmp_ge_u32 s32, 4
	s_cbranch_scc1 .Lattprio_0
	s_setprio 1
